# all three GEMM loops: LDS-DMA loads in scalar-base form (in-proj loop via 32-bit VGPR offsets and instruction offsets)
# baseline (speedup 1.0000x reference)
;     __device__ __forceinline__ void stage_rs(const Unit& u, int tid, int wid) const { stage_rs_lds(SS, rsl, u, tid, wid); }
;     __device__ __forceinline__ void stage_rs(const Unit& u, int tid, int wid) const { stage_rs_lds(SS, rsl, u, tid, wid); }
; #define PG8_STAGE(bufoff, gbase, voff) do { _Pragma("unroll") for (int _i = 0; _i < 2; ++_i) \
;         __builtin_amdgcn_global_load_lds((const unsigned*)((const char*)(gbase) + (voff)[_i]), (PG8_LAS unsigned*)(lds + (bufoff) + ldsw + _i * 8192), 16, 0, 0); } while (0)
; #define PG8_LDA(dst, b, h) do { _Pragma("unroll") for (int m = 0; m < 4; ++m) _Pragma("unroll") for (int k = 0; k < 2; ++k) dst[m][k] = *(const PG8_LAS bf16x8*)(lds + PG8_SA(b, h) + aoff + m * 2048 + k * 1024); } while (0)
; #define PG8_LDB(dst, b, h) do { _Pragma("unroll") for (int n = 0; n < 2; ++n) _Pragma("unroll") for (int k = 0; k < 2; ++k) dst[n][k] = *(const PG8_LAS bf16x8*)(lds + PG8_SB(b, h) + boff + n * 2048 + k * 1024); } while (0)
; #define PG8_BAR __builtin_amdgcn_s_barrier()
; template <class Epi, class Sched, bool ALIGN_EPI = false, bool SP2 = false>
; __device__ __forceinline__ void gemm_phase(PG8_LAS unsigned char* lds, const Gemm g, const Sched& S, const Epi& E, const int tid) {
;     ...
;             const bool last = (t == nt - 2);
;             if constexpr (Epi::RS_LDS) { if (t == nt - 4) E.stage_rs(cur, tid, wid); }
;             if constexpr (Epi::PREFETCH) { if (t >= nt - 8) E.prefetch(cur, lds, tid, wid, (t - (nt - 8)) >> 1); }
;             const char* a1 = cA + (size_t)(t + 1) * kstep;
;             const char* a2 = last ? nA : cA + (size_t)(t + 2) * kstep; const char* b2 = last ? nB : cB + (size_t)(t + 2) * kstep;
;             const char* a3 = a2 + kstep; const char* b3 = b2 + kstep;
;             if (last && has_next) S.a_ready(nxt);
;             if constexpr (SP2) {
;             PG8_LDB(B0, 0, 0); PG8_LDB(B1, 0, 1); PG8_SCHED; PG8_LDA(At, 0, 0); PG8_STAGE(PG8_SA(1, 1), a1 + hstep, voffA);
;             PG8_WAIT_V(8); PG8_WAIT_L(0); PG8_BAR; PG8_MMA(0, 0, At, B0); PG8_MMA(0, 1, At, B1); PG8_BAR; PG8_SCHED;
;     ...
; #pragma unroll
;         for (int a = 0; a < 2; ++a)
; #pragma unroll
;             for (int b = 0; b < 2; ++b)
; #pragma unroll
;                 for (int m = 0; m < 4; ++m)
; #pragma unroll
;                     for (int n = 0; n < 2; ++n) acc[a][b][m][n] = (f32x4){0.f, 0.f, 0.f, 0.f};
.LBB0_207:
	s_ashr_i32 s23, s22, 31
	s_lshl_b64 s[50:51], s[22:23], 19
	s_add_u32 s70, s45, s50
	s_addc_u32 s71, s80, s51
	s_and_b64 s[50:51], s[8:9], exec
	s_cselect_b32 s49, s71, s11
	s_cselect_b32 s78, s70, s10
	s_ashr_i32 s69, s68, 31
	s_lshl_b64 s[50:51], s[68:69], 19
	s_add_u32 s72, s81, s50
	s_addc_u32 s73, s82, s51
	s_and_b64 s[50:51], s[8:9], exec
	s_cselect_b32 s69, s73, s13
	s_cselect_b32 s79, s72, s12
	s_lshl_b32 s23, s48, 8
	s_waitcnt lgkmcnt(0)
	v_add_u32_e32 v2, s23, v157
	v_ashrrev_i32_e32 v3, 31, v2
	v_lshlrev_b64 v[4:5], 6, v[2:3]
	v_or_b32_e32 v2, 16, v2
	v_ashrrev_i32_e32 v3, 31, v2
	s_add_u32 s50, s10, 0x40080
	v_lshlrev_b64 v[2:3], 6, v[2:3]
	s_addc_u32 s51, s11, 0
	v_lshl_add_u64 v[144:145], v[138:139], 0, v[2:3]
	s_add_u32 vcc_lo, s12, 0x100
	v_mov_b32_e32 v2, 0
	v_lshl_add_u64 v[146:147], v[138:139], 0, v[4:5]
	v_add_u32_e32 v148, 0x3ff80, v140
	v_add_u32_e32 v150, 0x3ff80, v142
	s_addc_u32 vcc_hi, s13, 0
	s_mov_b32 s50, -2
	s_mov_b64 s[12:13], 0
	v_mov_b32_e32 v3, v2
	v_mov_b32_e32 v4, v2
	v_mov_b32_e32 v5, v2
	v_mov_b32_e32 v6, v2
	v_mov_b32_e32 v7, v2
	v_mov_b32_e32 v8, v2
	v_mov_b32_e32 v9, v2
	v_mov_b32_e32 v18, v2
	v_mov_b32_e32 v19, v2
	v_mov_b32_e32 v20, v2
	v_mov_b32_e32 v21, v2
	v_mov_b32_e32 v22, v2
	v_mov_b32_e32 v23, v2
	v_mov_b32_e32 v24, v2
	v_mov_b32_e32 v25, v2
	v_mov_b32_e32 v34, v2
	v_mov_b32_e32 v35, v2
	v_mov_b32_e32 v36, v2
	v_mov_b32_e32 v37, v2
	v_mov_b32_e32 v38, v2
	v_mov_b32_e32 v39, v2
	v_mov_b32_e32 v40, v2
	v_mov_b32_e32 v41, v2
	v_mov_b32_e32 v50, v2
	v_mov_b32_e32 v51, v2
	v_mov_b32_e32 v52, v2
	v_mov_b32_e32 v53, v2
	v_mov_b32_e32 v54, v2
	v_mov_b32_e32 v55, v2
	v_mov_b32_e32 v56, v2
	v_mov_b32_e32 v57, v2
	v_mov_b32_e32 v10, v2
	v_mov_b32_e32 v11, v2
	v_mov_b32_e32 v12, v2
	v_mov_b32_e32 v13, v2
	v_mov_b32_e32 v14, v2
	v_mov_b32_e32 v15, v2
	v_mov_b32_e32 v16, v2
	v_mov_b32_e32 v17, v2
	v_mov_b32_e32 v26, v2
	v_mov_b32_e32 v27, v2
	v_mov_b32_e32 v28, v2
	v_mov_b32_e32 v29, v2
	v_mov_b32_e32 v30, v2
	v_mov_b32_e32 v31, v2
	v_mov_b32_e32 v32, v2
	v_mov_b32_e32 v33, v2
	v_mov_b32_e32 v42, v2
	v_mov_b32_e32 v43, v2
	v_mov_b32_e32 v44, v2
	v_mov_b32_e32 v45, v2
	v_mov_b32_e32 v46, v2
	v_mov_b32_e32 v47, v2
	v_mov_b32_e32 v48, v2
	v_mov_b32_e32 v49, v2
	v_mov_b32_e32 v58, v2
	v_mov_b32_e32 v59, v2
	v_mov_b32_e32 v60, v2
	v_mov_b32_e32 v61, v2
	v_mov_b32_e32 v62, v2
	v_mov_b32_e32 v63, v2
	v_mov_b32_e32 v64, v2
	v_mov_b32_e32 v65, v2
	v_mov_b32_e32 v66, v2
	v_mov_b32_e32 v67, v2
	v_mov_b32_e32 v68, v2
	v_mov_b32_e32 v69, v2
	v_mov_b32_e32 v70, v2
	v_mov_b32_e32 v71, v2
	v_mov_b32_e32 v72, v2
	v_mov_b32_e32 v73, v2
	s_waitcnt vmcnt(0)
	v_mov_b32_e32 v82, v2
	v_mov_b32_e32 v83, v2
	v_mov_b32_e32 v84, v2
	v_mov_b32_e32 v85, v2
	v_mov_b32_e32 v86, v2
	v_mov_b32_e32 v87, v2
	v_mov_b32_e32 v88, v2
	v_mov_b32_e32 v89, v2
	v_mov_b32_e32 v98, v2
	v_mov_b32_e32 v99, v2
	v_mov_b32_e32 v100, v2
	v_mov_b32_e32 v101, v2
	v_mov_b32_e32 v102, v2
	v_mov_b32_e32 v103, v2
	v_mov_b32_e32 v104, v2
	v_mov_b32_e32 v105, v2
	v_mov_b32_e32 v114, v2
	v_mov_b32_e32 v115, v2
	v_mov_b32_e32 v116, v2
	v_mov_b32_e32 v117, v2
	v_mov_b32_e32 v118, v2
	v_mov_b32_e32 v119, v2
	v_mov_b32_e32 v120, v2
	v_mov_b32_e32 v121, v2
	v_mov_b32_e32 v74, v2
	v_mov_b32_e32 v75, v2
	v_mov_b32_e32 v76, v2
	v_mov_b32_e32 v77, v2
	v_mov_b32_e32 v78, v2
	v_mov_b32_e32 v79, v2
	v_mov_b32_e32 v80, v2
	v_mov_b32_e32 v81, v2
	v_mov_b32_e32 v90, v2
	v_mov_b32_e32 v91, v2
	v_mov_b32_e32 v92, v2
	v_mov_b32_e32 v93, v2
	v_mov_b32_e32 v94, v2
	v_mov_b32_e32 v95, v2
	v_mov_b32_e32 v96, v2
	v_mov_b32_e32 v97, v2
	v_mov_b32_e32 v106, v2
	v_mov_b32_e32 v107, v2
	v_mov_b32_e32 v108, v2
	v_mov_b32_e32 v109, v2
	v_mov_b32_e32 v110, v2
	v_mov_b32_e32 v111, v2
	v_mov_b32_e32 v112, v2
	v_mov_b32_e32 v113, v2
	v_mov_b32_e32 v122, v2
	v_mov_b32_e32 v123, v2
	v_mov_b32_e32 v124, v2
	v_mov_b32_e32 v125, v2
	v_mov_b32_e32 v126, v2
	v_mov_b32_e32 v127, v2
	v_mov_b32_e32 v128, v2
	v_mov_b32_e32 v129, v2
	s_branch .LBB0_209
.LBB0_208:
	s_add_u32 s38, s10, s12
	s_addc_u32 s39, s11, s13
	s_add_u32 s38, s38, 0x100
	s_addc_u32 s39, s39, 0
	s_add_u32 s51, vcc_lo, s12
	s_addc_u32 s74, vcc_hi, s13
	s_add_i32 s59, 0, 0x10000
	s_cmpk_eq_i32 s12, 0x700
	s_cselect_b32 s77, s49, s39
	s_cselect_b32 s76, s78, s38
	v_add_u32_e32 v0, s59, v153
	s_cselect_b32 s75, s69, s74
	s_cselect_b32 s74, s79, s51
	s_add_i32 s51, 0, 0x14000
	ds_read_b128 v[170:173], v0
	ds_read_b128 v[174:177], v0 offset:1024
	ds_read_b128 v[178:181], v0 offset:2048
	ds_read_b128 v[182:185], v0 offset:3072
	v_add_u32_e32 v0, s51, v153
	ds_read_b128 v[186:189], v0
	ds_read_b128 v[190:193], v0 offset:1024
	ds_read_b128 v[206:209], v0 offset:2048
	ds_read_b128 v[210:213], v0 offset:3072
	s_add_i32 m0, s84, 0xc000
	ds_read_b128 v[214:217], v167
	ds_read_b128 v[218:221], v167 offset:1024
	ds_read_b128 v[222:225], v167 offset:2048
	ds_read_b128 v[226:229], v167 offset:3072
	ds_read_b128 v[230:233], v167 offset:4096
	ds_read_b128 v[234:237], v167 offset:5120
	ds_read_b128 v[238:241], v167 offset:6144
	ds_read_b128 v[242:245], v167 offset:7168
	global_load_lds_dwordx4 v148, s[38:39]
	s_add_i32 m0, s84, 0xe000
	s_nop 0
	global_load_lds_dwordx4 v150, s[38:39]
	s_waitcnt vmcnt(8)
	s_waitcnt lgkmcnt(0)
	s_setprio 1
	s_barrier
; #define PG8_STAGE(bufoff, gbase, voff) do { _Pragma("unroll") for (int _i = 0; _i < 2; ++_i) \
;         __builtin_amdgcn_global_load_lds((const unsigned*)((const char*)(gbase) + (voff)[_i]), (PG8_LAS unsigned*)(lds + (bufoff) + ldsw + _i * 8192), 16, 0, 0); } while (0)
; #define PG8_LDA(dst, b, h) do { _Pragma("unroll") for (int m = 0; m < 4; ++m) _Pragma("unroll") for (int k = 0; k < 2; ++k) dst[m][k] = *(const PG8_LAS bf16x8*)(lds + PG8_SA(b, h) + aoff + m * 2048 + k * 1024); } while (0)
; #define PG8_MMA(ai, bj, At, Bt) do { __builtin_amdgcn_s_setprio(1); _Pragma("unroll") for (int m = 0; m < 4; ++m) _Pragma("unroll") for (int n = 0; n < 2; ++n) _Pragma("unroll") for (int k = 0; k < 2; ++k) \
;         acc[ai][bj][m][n] = __builtin_amdgcn_mfma_f32_16x16x32_bf16(Bt[n][k], At[m][k], acc[ai][bj][m][n], 0, 0, 0); __builtin_amdgcn_s_setprio(0); } while (0)
; #define PG8_WAIT_V(n) asm volatile("s_waitcnt vmcnt(" #n ")" ::: "memory")
; #define PG8_WAIT_L(n) asm volatile("s_waitcnt lgkmcnt(" #n ")" ::: "memory")
; #define PG8_BAR __builtin_amdgcn_s_barrier()
; #define PG8_SCHED __builtin_amdgcn_sched_barrier(0)
; template <class Epi, class Sched, bool ALIGN_EPI = false, bool SP2 = false>
; __device__ __forceinline__ void gemm_phase(PG8_LAS unsigned char* lds, const Gemm g, const Sched& S, const Epi& E, const int tid) {
;     ...
;             PG8_WAIT_V(8); PG8_WAIT_L(0); PG8_BAR; PG8_MMA(0, 0, At, B0); PG8_MMA(0, 1, At, B1); PG8_BAR; PG8_SCHED;
;             PG8_LDA(At, 0, 1); PG8_STAGE(PG8_SB(0, 0), b2, voffB); PG8_STAGE(PG8_SB(0, 1), b2 + hstep, voffB); PG8_STAGE(PG8_SA(0, 0), a2, voffA);
;             PG8_WAIT_V(8); PG8_WAIT_L(0); PG8_BAR; PG8_MMA(1, 0, At, B0); PG8_MMA(1, 1, At, B1); PG8_BAR; PG8_SCHED;
	v_mfma_f32_16x16x32_bf16 v[126:129], v[170:173], v[214:217], v[126:129]
	v_mfma_f32_16x16x32_bf16 v[122:125], v[178:181], v[214:217], v[122:125]
	v_mfma_f32_16x16x32_bf16 v[110:113], v[170:173], v[222:225], v[110:113]
	v_mfma_f32_16x16x32_bf16 v[106:109], v[178:181], v[222:225], v[106:109]
	v_mfma_f32_16x16x32_bf16 v[94:97], v[170:173], v[230:233], v[94:97]
	v_mfma_f32_16x16x32_bf16 v[90:93], v[178:181], v[230:233], v[90:93]
	v_mfma_f32_16x16x32_bf16 v[78:81], v[170:173], v[238:241], v[78:81]
	v_mfma_f32_16x16x32_bf16 v[74:77], v[178:181], v[238:241], v[74:77]
	v_mfma_f32_16x16x32_bf16 v[126:129], v[174:177], v[218:221], v[126:129]
	v_mfma_f32_16x16x32_bf16 v[122:125], v[182:185], v[218:221], v[122:125]
	v_mfma_f32_16x16x32_bf16 v[110:113], v[174:177], v[226:229], v[110:113]
	v_mfma_f32_16x16x32_bf16 v[106:109], v[182:185], v[226:229], v[106:109]
	v_mfma_f32_16x16x32_bf16 v[94:97], v[174:177], v[234:237], v[94:97]
	v_mfma_f32_16x16x32_bf16 v[90:93], v[182:185], v[234:237], v[90:93]
	v_mfma_f32_16x16x32_bf16 v[78:81], v[174:177], v[242:245], v[78:81]
	v_mfma_f32_16x16x32_bf16 v[74:77], v[182:185], v[242:245], v[74:77]
	v_mfma_f32_16x16x32_bf16 v[118:121], v[186:189], v[214:217], v[118:121]
	v_mfma_f32_16x16x32_bf16 v[114:117], v[206:209], v[214:217], v[114:117]
	v_mfma_f32_16x16x32_bf16 v[102:105], v[186:189], v[222:225], v[102:105]
	v_mfma_f32_16x16x32_bf16 v[98:101], v[206:209], v[222:225], v[98:101]
	v_mfma_f32_16x16x32_bf16 v[86:89], v[186:189], v[230:233], v[86:89]
	v_mfma_f32_16x16x32_bf16 v[82:85], v[206:209], v[230:233], v[82:85]
	v_mfma_f32_16x16x32_bf16 v[70:73], v[186:189], v[238:241], v[70:73]
	v_mfma_f32_16x16x32_bf16 v[66:69], v[206:209], v[238:241], v[66:69]
	v_mfma_f32_16x16x32_bf16 v[118:121], v[190:193], v[218:221], v[118:121]
	v_mfma_f32_16x16x32_bf16 v[114:117], v[210:213], v[218:221], v[114:117]
	v_mfma_f32_16x16x32_bf16 v[102:105], v[190:193], v[226:229], v[102:105]
	v_mfma_f32_16x16x32_bf16 v[98:101], v[210:213], v[226:229], v[98:101]
	v_mfma_f32_16x16x32_bf16 v[86:89], v[190:193], v[234:237], v[86:89]
	v_mfma_f32_16x16x32_bf16 v[82:85], v[210:213], v[234:237], v[82:85]
	v_mfma_f32_16x16x32_bf16 v[70:73], v[190:193], v[242:245], v[70:73]
	v_mfma_f32_16x16x32_bf16 v[66:69], v[210:213], v[242:245], v[66:69]
	s_setprio 0
	s_barrier
	s_add_i32 s38, s59, s83
	s_mov_b32 m0, s38
	ds_read_b128 v[214:217], v167 offset:16384
	ds_read_b128 v[218:221], v167 offset:17408
	ds_read_b128 v[222:225], v167 offset:18432
	ds_read_b128 v[226:229], v167 offset:19456
	ds_read_b128 v[230:233], v167 offset:20480
	ds_read_b128 v[234:237], v167 offset:21504
	ds_read_b128 v[238:241], v167 offset:22528
	ds_read_b128 v[242:245], v167 offset:23552
	global_load_lds_dwordx4 v134, s[74:75]
	s_add_i32 m0, s38, 0x2000
	s_add_u32 s38, s74, 0x40000
	s_addc_u32 s39, s75, 0
	s_add_i32 s51, s51, s83
	global_load_lds_dwordx4 v130, s[74:75]
	s_mov_b32 m0, s51
	s_nop 0
	global_load_lds_dwordx4 v134, s[38:39]
	s_add_i32 m0, s51, 0x2000
	s_nop 0
	global_load_lds_dwordx4 v130, s[38:39]
	s_mov_b32 m0, s84
	s_nop 0
	global_load_lds_dwordx4 v136, s[76:77]
	s_mov_b32 m0, s85
	s_nop 0
	global_load_lds_dwordx4 v132, s[76:77]
	s_waitcnt vmcnt(8)
	s_waitcnt lgkmcnt(0)
	s_setprio 1
	s_barrier
	v_mfma_f32_16x16x32_bf16 v[62:65], v[170:173], v[214:217], v[62:65]
	v_mfma_f32_16x16x32_bf16 v[58:61], v[178:181], v[214:217], v[58:61]
	v_mfma_f32_16x16x32_bf16 v[46:49], v[170:173], v[222:225], v[46:49]
	v_mfma_f32_16x16x32_bf16 v[42:45], v[178:181], v[222:225], v[42:45]
	v_mfma_f32_16x16x32_bf16 v[30:33], v[170:173], v[230:233], v[30:33]
	v_mfma_f32_16x16x32_bf16 v[26:29], v[178:181], v[230:233], v[26:29]
	v_mfma_f32_16x16x32_bf16 v[14:17], v[170:173], v[238:241], v[14:17]
	v_mfma_f32_16x16x32_bf16 v[10:13], v[178:181], v[238:241], v[10:13]
	v_mfma_f32_16x16x32_bf16 v[62:65], v[174:177], v[218:221], v[62:65]
	v_mfma_f32_16x16x32_bf16 v[58:61], v[182:185], v[218:221], v[58:61]
	v_mfma_f32_16x16x32_bf16 v[46:49], v[174:177], v[226:229], v[46:49]
	v_mfma_f32_16x16x32_bf16 v[42:45], v[182:185], v[226:229], v[42:45]
	v_mfma_f32_16x16x32_bf16 v[30:33], v[174:177], v[234:237], v[30:33]
	v_mfma_f32_16x16x32_bf16 v[26:29], v[182:185], v[234:237], v[26:29]
	v_mfma_f32_16x16x32_bf16 v[14:17], v[174:177], v[242:245], v[14:17]
	v_mfma_f32_16x16x32_bf16 v[10:13], v[182:185], v[242:245], v[10:13]
	v_mfma_f32_16x16x32_bf16 v[54:57], v[186:189], v[214:217], v[54:57]
	v_mfma_f32_16x16x32_bf16 v[50:53], v[206:209], v[214:217], v[50:53]
	v_mfma_f32_16x16x32_bf16 v[38:41], v[186:189], v[222:225], v[38:41]
	v_mfma_f32_16x16x32_bf16 v[34:37], v[206:209], v[222:225], v[34:37]
	v_mfma_f32_16x16x32_bf16 v[22:25], v[186:189], v[230:233], v[22:25]
	v_mfma_f32_16x16x32_bf16 v[18:21], v[206:209], v[230:233], v[18:21]
	v_mfma_f32_16x16x32_bf16 v[6:9], v[186:189], v[238:241], v[6:9]
	v_mfma_f32_16x16x32_bf16 v[2:5], v[206:209], v[238:241], v[2:5]
	v_mfma_f32_16x16x32_bf16 v[54:57], v[190:193], v[218:221], v[54:57]
	v_mfma_f32_16x16x32_bf16 v[50:53], v[210:213], v[218:221], v[50:53]
	v_mfma_f32_16x16x32_bf16 v[38:41], v[190:193], v[226:229], v[38:41]
	v_mfma_f32_16x16x32_bf16 v[34:37], v[210:213], v[226:229], v[34:37]
	v_mfma_f32_16x16x32_bf16 v[22:25], v[190:193], v[234:237], v[22:25]
	v_mfma_f32_16x16x32_bf16 v[18:21], v[210:213], v[234:237], v[18:21]
	v_mfma_f32_16x16x32_bf16 v[6:9], v[190:193], v[242:245], v[6:9]
	v_mfma_f32_16x16x32_bf16 v[2:5], v[210:213], v[242:245], v[2:5]
	s_setprio 0
	s_barrier
; #define PG8_STAGE(bufoff, gbase, voff) do { _Pragma("unroll") for (int _i = 0; _i < 2; ++_i) \
;         __builtin_amdgcn_global_load_lds((const unsigned*)((const char*)(gbase) + (voff)[_i]), (PG8_LAS unsigned*)(lds + (bufoff) + ldsw + _i * 8192), 16, 0, 0); } while (0)
; #define PG8_LDA(dst, b, h) do { _Pragma("unroll") for (int m = 0; m < 4; ++m) _Pragma("unroll") for (int k = 0; k < 2; ++k) dst[m][k] = *(const PG8_LAS bf16x8*)(lds + PG8_SA(b, h) + aoff + m * 2048 + k * 1024); } while (0)
; #define PG8_LDB(dst, b, h) do { _Pragma("unroll") for (int n = 0; n < 2; ++n) _Pragma("unroll") for (int k = 0; k < 2; ++k) dst[n][k] = *(const PG8_LAS bf16x8*)(lds + PG8_SB(b, h) + boff + n * 2048 + k * 1024); } while (0)
; #define PG8_MMA(ai, bj, At, Bt) do { __builtin_amdgcn_s_setprio(1); _Pragma("unroll") for (int m = 0; m < 4; ++m) _Pragma("unroll") for (int n = 0; n < 2; ++n) _Pragma("unroll") for (int k = 0; k < 2; ++k) \
;         acc[ai][bj][m][n] = __builtin_amdgcn_mfma_f32_16x16x32_bf16(Bt[n][k], At[m][k], acc[ai][bj][m][n], 0, 0, 0); __builtin_amdgcn_s_setprio(0); } while (0)
; #define PG8_WAIT_V(n) asm volatile("s_waitcnt vmcnt(" #n ")" ::: "memory")
; #define PG8_WAIT_L(n) asm volatile("s_waitcnt lgkmcnt(" #n ")" ::: "memory")
; #define PG8_BAR __builtin_amdgcn_s_barrier()
; #define PG8_SCHED __builtin_amdgcn_sched_barrier(0)
; template <class Epi, class Sched, bool ALIGN_EPI = false, bool SP2 = false>
; __device__ __forceinline__ void gemm_phase(PG8_LAS unsigned char* lds, const Gemm g, const Sched& S, const Epi& E, const int tid) {
;     ...
;             PG8_LDB(B0, 1, 0); PG8_LDB(B1, 1, 1); PG8_SCHED; PG8_LDA(At, 1, 0); PG8_STAGE(PG8_SA(0, 1), a2 + hstep, voffA);
;             PG8_WAIT_V(8); PG8_WAIT_L(0); PG8_BAR; PG8_MMA(0, 0, At, B0); PG8_MMA(0, 1, At, B1); PG8_BAR; PG8_SCHED;
;             PG8_LDA(At, 1, 1); PG8_STAGE(PG8_SB(1, 0), b3, voffB); PG8_STAGE(PG8_SB(1, 1), b3 + hstep, voffB); PG8_STAGE(PG8_SA(1, 0), a3, voffA);
;             PG8_WAIT_V(8); PG8_WAIT_L(0); PG8_BAR; PG8_MMA(1, 0, At, B0); PG8_MMA(1, 1, At, B1); PG8_BAR; PG8_SCHED;
	s_add_i32 s51, 0, 0x18000
	v_add_u32_e32 v0, s51, v153
	s_add_i32 s59, 0, 0x1c000
	ds_read_b128 v[170:173], v0
	ds_read_b128 v[174:177], v0 offset:1024
	ds_read_b128 v[178:181], v0 offset:2048
	ds_read_b128 v[182:185], v0 offset:3072
	v_add_u32_e32 v0, s59, v153
	ds_read_b128 v[186:189], v0
	ds_read_b128 v[190:193], v0 offset:1024
	ds_read_b128 v[206:209], v0 offset:2048
	ds_read_b128 v[210:213], v0 offset:3072
	s_add_u32 s38, s76, 0x40000
	s_addc_u32 s39, s77, 0
	s_mov_b32 m0, s86
	ds_read_b128 v[214:217], v167 offset:32768
	ds_read_b128 v[218:221], v167 offset:33792
	ds_read_b128 v[222:225], v167 offset:34816
	ds_read_b128 v[226:229], v167 offset:35840
	ds_read_b128 v[230:233], v167 offset:36864
	ds_read_b128 v[234:237], v167 offset:37888
	ds_read_b128 v[238:241], v167 offset:38912
	ds_read_b128 v[242:245], v167 offset:39936
	global_load_lds_dwordx4 v136, s[38:39]
	s_mov_b32 m0, s87
	s_nop 0
	global_load_lds_dwordx4 v132, s[38:39]
	s_waitcnt vmcnt(8)
	s_waitcnt lgkmcnt(0)
	s_setprio 1
	s_barrier
	v_mfma_f32_16x16x32_bf16 v[126:129], v[170:173], v[214:217], v[126:129]
	v_mfma_f32_16x16x32_bf16 v[122:125], v[178:181], v[214:217], v[122:125]
	v_mfma_f32_16x16x32_bf16 v[110:113], v[170:173], v[222:225], v[110:113]
	v_mfma_f32_16x16x32_bf16 v[106:109], v[178:181], v[222:225], v[106:109]
	v_mfma_f32_16x16x32_bf16 v[94:97], v[170:173], v[230:233], v[94:97]
	v_mfma_f32_16x16x32_bf16 v[90:93], v[178:181], v[230:233], v[90:93]
	v_mfma_f32_16x16x32_bf16 v[78:81], v[170:173], v[238:241], v[78:81]
	v_mfma_f32_16x16x32_bf16 v[74:77], v[178:181], v[238:241], v[74:77]
	v_mfma_f32_16x16x32_bf16 v[126:129], v[174:177], v[218:221], v[126:129]
	v_mfma_f32_16x16x32_bf16 v[122:125], v[182:185], v[218:221], v[122:125]
	v_mfma_f32_16x16x32_bf16 v[110:113], v[174:177], v[226:229], v[110:113]
	v_mfma_f32_16x16x32_bf16 v[106:109], v[182:185], v[226:229], v[106:109]
	v_mfma_f32_16x16x32_bf16 v[94:97], v[174:177], v[234:237], v[94:97]
	v_mfma_f32_16x16x32_bf16 v[90:93], v[182:185], v[234:237], v[90:93]
	v_mfma_f32_16x16x32_bf16 v[78:81], v[174:177], v[242:245], v[78:81]
	v_mfma_f32_16x16x32_bf16 v[74:77], v[182:185], v[242:245], v[74:77]
	v_mfma_f32_16x16x32_bf16 v[118:121], v[186:189], v[214:217], v[118:121]
	v_mfma_f32_16x16x32_bf16 v[114:117], v[206:209], v[214:217], v[114:117]
	v_mfma_f32_16x16x32_bf16 v[102:105], v[186:189], v[222:225], v[102:105]
	v_mfma_f32_16x16x32_bf16 v[98:101], v[206:209], v[222:225], v[98:101]
	v_mfma_f32_16x16x32_bf16 v[86:89], v[186:189], v[230:233], v[86:89]
	v_mfma_f32_16x16x32_bf16 v[82:85], v[206:209], v[230:233], v[82:85]
	v_mfma_f32_16x16x32_bf16 v[70:73], v[186:189], v[238:241], v[70:73]
	v_mfma_f32_16x16x32_bf16 v[66:69], v[206:209], v[238:241], v[66:69]
	v_mfma_f32_16x16x32_bf16 v[118:121], v[190:193], v[218:221], v[118:121]
	v_mfma_f32_16x16x32_bf16 v[114:117], v[210:213], v[218:221], v[114:117]
	v_mfma_f32_16x16x32_bf16 v[102:105], v[190:193], v[226:229], v[102:105]
	v_mfma_f32_16x16x32_bf16 v[98:101], v[210:213], v[226:229], v[98:101]
	v_mfma_f32_16x16x32_bf16 v[86:89], v[190:193], v[234:237], v[86:89]
	v_mfma_f32_16x16x32_bf16 v[82:85], v[210:213], v[234:237], v[82:85]
	v_mfma_f32_16x16x32_bf16 v[70:73], v[190:193], v[242:245], v[70:73]
	v_mfma_f32_16x16x32_bf16 v[66:69], v[210:213], v[242:245], v[66:69]
	s_setprio 0
	s_barrier
	s_add_i32 s38, s51, s83
	s_add_i32 m0, s38, 0xffffff80
	ds_read_b128 v[214:217], v167 offset:49152
	ds_read_b128 v[218:221], v167 offset:50176
	ds_read_b128 v[222:225], v167 offset:51200
	ds_read_b128 v[226:229], v167 offset:52224
	ds_read_b128 v[230:233], v167 offset:53248
	ds_read_b128 v[234:237], v167 offset:54272
	ds_read_b128 v[238:241], v167 offset:55296
	ds_read_b128 v[242:245], v167 offset:56320
	global_load_lds_dwordx4 v134, s[74:75] offset:128
	s_add_i32 m0, s38, 0x1f80
	s_add_u32 s38, s74, 0x40080
	s_addc_u32 s39, s75, 0
	s_add_i32 s51, s59, s83
	global_load_lds_dwordx4 v130, s[74:75] offset:128
	s_mov_b32 m0, s51
	s_nop 0
	global_load_lds_dwordx4 v134, s[38:39]
	s_add_i32 m0, s51, 0x2000
	s_nop 0
	global_load_lds_dwordx4 v130, s[38:39]
	s_add_i32 m0, s88, 0xffffff80
	s_nop 0
	global_load_lds_dwordx4 v136, s[76:77] offset:128
	s_add_i32 m0, s89, 0xffffff80
	s_nop 0
	global_load_lds_dwordx4 v132, s[76:77] offset:128
	s_waitcnt vmcnt(8)
	s_waitcnt lgkmcnt(0)
	s_setprio 1
	s_barrier
	v_mfma_f32_16x16x32_bf16 v[62:65], v[170:173], v[214:217], v[62:65]
	v_mfma_f32_16x16x32_bf16 v[58:61], v[178:181], v[214:217], v[58:61]
	v_mfma_f32_16x16x32_bf16 v[46:49], v[170:173], v[222:225], v[46:49]
	v_mfma_f32_16x16x32_bf16 v[42:45], v[178:181], v[222:225], v[42:45]
	v_mfma_f32_16x16x32_bf16 v[30:33], v[170:173], v[230:233], v[30:33]
	v_mfma_f32_16x16x32_bf16 v[26:29], v[178:181], v[230:233], v[26:29]
	v_mfma_f32_16x16x32_bf16 v[14:17], v[170:173], v[238:241], v[14:17]
	v_mfma_f32_16x16x32_bf16 v[10:13], v[178:181], v[238:241], v[10:13]
	v_mfma_f32_16x16x32_bf16 v[62:65], v[174:177], v[218:221], v[62:65]
	v_mfma_f32_16x16x32_bf16 v[58:61], v[182:185], v[218:221], v[58:61]
	v_mfma_f32_16x16x32_bf16 v[46:49], v[174:177], v[226:229], v[46:49]
	v_mfma_f32_16x16x32_bf16 v[42:45], v[182:185], v[226:229], v[42:45]
	v_mfma_f32_16x16x32_bf16 v[30:33], v[174:177], v[234:237], v[30:33]
	v_mfma_f32_16x16x32_bf16 v[26:29], v[182:185], v[234:237], v[26:29]
	v_mfma_f32_16x16x32_bf16 v[14:17], v[174:177], v[242:245], v[14:17]
	v_mfma_f32_16x16x32_bf16 v[10:13], v[182:185], v[242:245], v[10:13]
	v_mfma_f32_16x16x32_bf16 v[54:57], v[186:189], v[214:217], v[54:57]
	v_mfma_f32_16x16x32_bf16 v[50:53], v[206:209], v[214:217], v[50:53]
	v_mfma_f32_16x16x32_bf16 v[38:41], v[186:189], v[222:225], v[38:41]
	v_mfma_f32_16x16x32_bf16 v[34:37], v[206:209], v[222:225], v[34:37]
	v_mfma_f32_16x16x32_bf16 v[22:25], v[186:189], v[230:233], v[22:25]
	v_mfma_f32_16x16x32_bf16 v[18:21], v[206:209], v[230:233], v[18:21]
	v_mfma_f32_16x16x32_bf16 v[6:9], v[186:189], v[238:241], v[6:9]
	v_mfma_f32_16x16x32_bf16 v[2:5], v[206:209], v[238:241], v[2:5]
	v_mfma_f32_16x16x32_bf16 v[54:57], v[190:193], v[218:221], v[54:57]
	v_mfma_f32_16x16x32_bf16 v[50:53], v[210:213], v[218:221], v[50:53]
	v_mfma_f32_16x16x32_bf16 v[38:41], v[190:193], v[226:229], v[38:41]
	v_mfma_f32_16x16x32_bf16 v[34:37], v[210:213], v[226:229], v[34:37]
	v_mfma_f32_16x16x32_bf16 v[22:25], v[190:193], v[234:237], v[22:25]
	v_mfma_f32_16x16x32_bf16 v[18:21], v[210:213], v[234:237], v[18:21]
	v_mfma_f32_16x16x32_bf16 v[6:9], v[190:193], v[242:245], v[6:9]
	v_mfma_f32_16x16x32_bf16 v[2:5], v[210:213], v[242:245], v[2:5]
	s_setprio 0
	s_barrier
	s_add_i32 s50, s50, 2
	s_add_u32 s12, s12, 0x100
	s_addc_u32 s13, s13, 0
	s_cmp_gt_u32 s50, 13
	s_cbranch_scc1 .LBB0_211
